# v18 + nt (non-temporal) on the no-reuse streaming loads of merge/conv/LN1/LN2 so they do not evict dirty write lines from L2
# speedup vs baseline: 1.0037x; 1.0024x over previous
; DI void phase_ln(const void* srcv, const int srcmode, const bf16_t* xres,
;                  const float* g, const float* b, float* dstf, bf16_t* dstb, int ntok, int tid,
;                  unsigned char* smem, const float* wg, const float* bias16, float* gpre) {
;     ...
;     f32x4 gvv[2][2], bvv[2][2];
; #pragma unroll
;     for (int q = 0; q < 2; ++q)
; #pragma unroll
;         for (int h = 0; h < 2; ++h) { gvv[q][h] = *(const f32x4*)(g + q * 512 + lane * 8 + h * 4); bvv[q][h] = *(const f32x4*)(b + q * 512 + lane * 8 + h * 4); }
;     u32x4 na[2], nb[2];
;     ...
;     {
;         const int r0 = blockIdx.x * 8 + wid;
;         if (r0 < ntok) LN_LOAD(r0);
;     }
.LBB0_151:
	s_and_saveexec_b64 s[46:47], s[36:37]
	s_cbranch_execz .LBB0_150
	s_mov_b32 s13, s67
	s_xor_b64 s[48:49], s[20:21], -1
	v_readlane_b32 s52, v253, 3
	s_and_b64 s[30:31], s[20:21], exec
	v_readlane_b32 s56, v253, 7
	v_readlane_b32 s57, v253, 8
	v_readlane_b32 s58, v253, 9
	v_readlane_b32 s59, v253, 10
	s_cselect_b32 s31, s26, s57
	s_cselect_b32 s30, s23, s56
	s_cselect_b32 s35, s28, s59
	s_cselect_b32 s34, s27, s58
	global_load_dwordx4 v[2:5], v80, s[30:31] offset:16 nt
	global_load_dwordx4 v[6:9], v80, s[30:31] nt
	global_load_dwordx4 v[10:13], v80, s[34:35] offset:16 nt
	global_load_dwordx4 v[14:17], v80, s[34:35] nt
	global_load_dwordx4 v[18:21], v80, s[30:31] offset:2064 nt
	global_load_dwordx4 v[22:25], v80, s[30:31] offset:2048 nt
	global_load_dwordx4 v[26:29], v80, s[34:35] offset:2064 nt
	global_load_dwordx4 v[30:33], v80, s[34:35] offset:2048 nt
	v_readlane_b32 s30, v255, 7
	v_readlane_b32 s31, v255, 8
	s_cselect_b32 s39, s31, s8
	s_cselect_b32 s38, s30, s9
	s_waitcnt vmcnt(9)
	v_lshl_add_u64 v[40:41], v[60:61], 1, s[38:39]
	v_mov_b32_e32 v81, v1
	v_lshl_add_u64 v[34:35], v[40:41], 0, v[62:63]
	s_waitcnt vmcnt(8)
	v_lshl_add_u64 v[46:47], v[34:35], 0, v[80:81]
	s_mov_b64 s[40:41], -1
	s_and_b64 vcc, exec, s[48:49]
	v_readlane_b32 s53, v253, 4
	v_readlane_b32 s54, v253, 5
	v_readlane_b32 s55, v253, 6
	v_readlane_b32 s60, v253, 11
	v_readlane_b32 s61, v253, 12
	v_readlane_b32 s62, v253, 13
	v_readlane_b32 s63, v253, 14
	v_readlane_b32 s64, v253, 15
	v_readlane_b32 s65, v253, 16
	v_readlane_b32 s66, v253, 17
	v_readlane_b32 s67, v253, 18
	s_cbranch_vccz .LBB0_154
	global_load_dwordx4 v[34:37], v[46:47], off nt
	v_lshl_add_u64 v[38:39], v[46:47], 0, 16
	s_mov_b64 s[40:41], 0
.LBB0_154:
	s_andn2_b64 vcc, exec, s[40:41]
	v_lshl_add_u64 v[50:51], v[40:41], 0, v[0:1]
	s_cbranch_vccnz .LBB0_156
	global_load_dwordx4 v[34:37], v[50:51], off nt
	v_mov_b64_e32 v[38:39], v[64:65]
.LBB0_156:
	global_load_dwordx4 v[38:41], v[38:39], off nt
	s_mov_b64 s[40:41], -1
	s_and_b64 vcc, exec, s[48:49]
	s_mov_b32 s67, s13
	s_cbranch_vccz .LBB0_158
	global_load_dwordx4 v[42:45], v[46:47], off offset:2048 nt
	s_mov_b64 s[30:31], 0x810
	v_lshl_add_u64 v[48:49], v[46:47], 0, s[30:31]
	s_mov_b64 s[40:41], 0
.LBB0_158:
	s_andn2_b64 vcc, exec, s[40:41]
	s_cbranch_vccnz .LBB0_160
	global_load_dwordx4 v[42:45], v[50:51], off offset:1024 nt
	v_mov_b64_e32 v[48:49], v[66:67]
.LBB0_160:
	global_load_dwordx4 v[46:49], v[48:49], off nt
	s_and_b64 s[30:31], s[20:21], s[0:1]
	s_and_b64 s[30:31], s[30:31], exec
	v_readlane_b32 s30, v254, 63
	v_readlane_b32 s31, v255, 0
	s_cselect_b32 s31, s31, 0
	s_cselect_b32 s30, s30, 0
	s_and_b64 s[34:35], s[20:21], exec
	s_cselect_b32 s35, s3, s15
	s_cselect_b32 s34, s2, s14
	s_cmp_lg_u64 s[30:31], 0
	s_cselect_b64 s[52:53], -1, 0
	s_cmp_lg_u64 s[34:35], 0
	v_lshl_add_u64 v[50:51], s[34:35], 0, v[62:63]
	s_mov_b64 s[34:35], 0x400
	s_mov_b64 s[50:51], 0
	s_cselect_b64 s[54:55], -1, 0
	v_lshl_add_u64 v[82:83], v[50:51], 0, s[34:35]
	v_lshl_add_u64 v[84:85], s[30:31], 0, v[74:75]
	v_lshl_add_u64 v[86:87], s[38:39], 0, v[76:77]
	v_lshl_add_u64 v[88:89], s[38:39], 0, v[78:79]
	v_mov_b64_e32 v[90:91], v[70:71]
	v_mov_b32_e32 v92, v58
	s_branch .LBB0_162

; DI void phase_ln(const void* srcv, const int srcmode, const bf16_t* xres,
;                  const float* g, const float* b, float* dstf, bf16_t* dstb, int ntok, int tid,
;                  unsigned char* smem, const float* wg, const float* bias16, float* gpre) {
;     ...
;         if (row + rstride < ntok) LN_LOAD(row + rstride);
.LBB0_170:
	v_add_u32_e32 v92, s12, v92
	v_cmp_gt_i32_e32 vcc, s10, v92
	v_cmp_le_i32_e64 s[38:39], s10, v92
	s_and_saveexec_b64 s[40:41], vcc
	s_cbranch_execz .LBB0_180
	s_waitcnt vmcnt(0)
	v_lshl_add_u64 v[46:47], v[88:89], 0, v[72:73]
	s_mov_b64 s[58:59], -1
	s_and_b64 vcc, exec, s[48:49]
	s_cbranch_vccz .LBB0_173
	global_load_dwordx4 v[34:37], v[46:47], off nt
	v_lshl_add_u64 v[38:39], v[46:47], 0, 16
	s_mov_b64 s[58:59], 0
.LBB0_173:
	v_ashrrev_i32_e32 v93, 31, v92
	v_lshlrev_b64 v[40:41], 11, v[92:93]
	v_lshl_add_u64 v[48:49], v[86:87], 0, v[90:91]
	s_andn2_b64 vcc, exec, s[58:59]
	v_lshl_add_u64 v[42:43], v[68:69], 0, v[40:41]
	s_cbranch_vccnz .LBB0_175
	global_load_dwordx4 v[34:37], v[48:49], off nt
	v_mov_b64_e32 v[38:39], v[42:43]
.LBB0_175:
	global_load_dwordx4 v[38:41], v[38:39], off nt
	s_and_b64 vcc, exec, s[48:49]
	s_cbranch_vccz .LBB0_177
	global_load_dwordx4 v[42:45], v[46:47], off offset:2048 nt
	s_mov_b64 s[30:31], 0x810
	v_lshl_add_u64 v[46:47], v[46:47], 0, s[30:31]
	s_cbranch_execz .LBB0_178
	s_branch .LBB0_179

; DI void phase_ln(const void* srcv, const int srcmode, const bf16_t* xres,
;                  const float* g, const float* b, float* dstf, bf16_t* dstb, int ntok, int tid,
;                  unsigned char* smem, const float* wg, const float* bias16, float* gpre) {
;     ...
;         if (row + rstride < ntok) LN_LOAD(row + rstride);
.LBB0_178:
	global_load_dwordx4 v[42:45], v[48:49], off offset:1024 nt
.LBB0_179:
	s_nop 0
	global_load_dwordx4 v[46:49], v[46:47], off nt

; DI void phase_conv(const Params& p, int layer, int ntok, int S, int tid) {
;     ...
;     for (int task = blockIdx.x * 8 + wid; task < ntask; task += gridDim.x * 8) {
;         const int cwv = task % NCW, seg = task / NCW;
;         const int c = (cwv * 64 + lane) * 4;
;         const int t0 = seg * SEG, pos0 = t0 % S;
;         const f32x4 wv0 = *(const f32x4*)(cw + c), wv1 = *(const f32x4*)(cw + NUP + c), wv2 = *(const f32x4*)(cw + 2 * NUP + c), bv = *(const f32x4*)(cbias + c);
;         const f32x4 wg0 = *(const f32x4*)(cw + DFF + c), wg1 = *(const f32x4*)(cw + NUP + DFF + c), wg2 = *(const f32x4*)(cw + 2 * NUP + DFF + c), bg = *(const f32x4*)(cbias + DFF + c);
;         const bf16_t* hv = p.hu + (size_t)t0 * NUP + c; const bf16_t* hg = hv + DFF;
;         bf16_t* op = p.ff + (size_t)t0 * DFF + c;
;         const u32x2 z = {0u, 0u};
;         u32x2 rv[SEG + 2], rg[SEG + 2];
;         rv[0] = pos0 > 0 ? *(const u32x2*)(hv - NUP) : z; rg[0] = pos0 > 0 ? *(const u32x2*)(hg - NUP) : z;
; #pragma unroll
;         for (int i = 0; i < SEG; ++i) { rv[i + 1] = *(const u32x2*)(hv + (size_t)i * NUP); rg[i + 1] = *(const u32x2*)(hg + (size_t)i * NUP); }
;         { const bool hn = (pos0 + SEG - 1) < S - 1; rv[SEG + 1] = hn ? *(const u32x2*)(hv + (size_t)SEG * NUP) : z; rg[SEG + 1] = hn ? *(const u32x2*)(hg + (size_t)SEG * NUP) : z; }
.LBB0_219:
	s_mov_b32 s0, 0x2e8ba2e9
	v_mul_hi_i32 v2, v110, s0
	v_lshrrev_b32_e32 v3, 31, v2
	v_ashrrev_i32_e32 v2, 1, v2
	v_add_u32_e32 v34, v2, v3
	s_movk_i32 s0, 0xf500
	v_mad_u64_u32 v[36:37], s[0:1], v34, s0, v[0:1]
	v_ashrrev_i32_e32 v37, 31, v36
	v_lshlrev_b64 v[10:11], 2, v[36:37]
	v_lshl_add_u64 v[2:3], s[18:19], 0, v[10:11]
	v_lshl_add_u64 v[4:5], s[38:39], 0, v[10:11]
	global_load_dwordx4 v[26:29], v[2:3], off nt
	global_load_dwordx4 v[30:33], v[4:5], off nt
	v_lshl_add_u64 v[2:3], s[40:41], 0, v[10:11]
	global_load_dwordx4 v[18:21], v[2:3], off nt
	v_lshl_add_u64 v[2:3], s[36:37], 0, v[10:11]
	global_load_dwordx4 v[22:25], v[2:3], off nt
	v_lshl_add_u64 v[2:3], s[46:47], 0, v[10:11]
	v_lshl_add_u64 v[6:7], s[78:79], 0, v[10:11]
	global_load_dwordx4 v[2:5], v[2:3], off nt
	s_nop 0
	global_load_dwordx4 v[14:17], v[6:7], off nt
	v_lshl_add_u64 v[6:7], s[94:95], 0, v[10:11]
	v_lshl_add_u64 v[10:11], s[96:97], 0, v[10:11]
	global_load_dwordx4 v[6:9], v[6:7], off nt
	v_lshlrev_b32_e32 v112, 4, v34
	global_load_dwordx4 v[10:13], v[10:11], off nt
	s_waitcnt vmcnt(0)
	v_sub_u32_e32 v38, 0, v112
	v_max_i32_e32 v38, v112, v38
	v_mul_hi_u32 v39, v38, v111
	v_mul_lo_u32 v39, v39, s23
	v_sub_u32_e32 v38, v38, v39
	v_subrev_u32_e32 v39, s23, v38
	v_cmp_le_u32_e32 vcc, s23, v38
	v_ashrrev_i32_e32 v35, 31, v112
	v_readlane_b32 s0, v255, 10
	v_cndmask_b32_e32 v38, v38, v39, vcc
	v_subrev_u32_e32 v39, s23, v38
	v_cmp_le_u32_e32 vcc, s23, v38
	v_readlane_b32 s1, v255, 11
	v_mov_b32_e32 v34, 0
	v_cndmask_b32_e32 v38, v38, v39, vcc
	v_xor_b32_e32 v38, v38, v35
	v_sub_u32_e32 v35, v38, v35
	v_mov_b64_e32 v[38:39], s[0:1]
	s_movk_i32 s0, 0x2c00
	v_mad_i64_i32 v[38:39], s[0:1], v112, s0, v[38:39]
	v_lshl_add_u64 v[100:101], v[36:37], 1, v[38:39]
	v_cmp_lt_i32_e32 vcc, 0, v35
	v_mov_b32_e32 v98, 0
	v_mov_b32_e32 v99, 0
	v_mov_b32_e32 v96, 0
	v_mov_b32_e32 v97, 0
	s_and_saveexec_b64 s[0:1], vcc
	s_cbranch_execz .LBB0_221
	v_add_co_u32_e32 v38, vcc, 0xffffe000, v100
	s_nop 1
	v_addc_co_u32_e32 v39, vcc, -1, v101, vcc
	v_add_co_u32_e32 v40, vcc, 0xfffff000, v100
	s_nop 1
	v_addc_co_u32_e32 v41, vcc, -1, v101, vcc
	global_load_dwordx2 v[98:99], v[38:39], off offset:-3072 nt
	global_load_dwordx2 v[96:97], v[40:41], off offset:-1536 nt
; DI void phase_conv(const Params& p, int layer, int ntok, int S, int tid) {
;     ...
;         for (int i = 0; i < SEG; ++i) { rv[i + 1] = *(const u32x2*)(hv + (size_t)i * NUP); rg[i + 1] = *(const u32x2*)(hg + (size_t)i * NUP); }
;         { const bool hn = (pos0 + SEG - 1) < S - 1; rv[SEG + 1] = hn ? *(const u32x2*)(hv + (size_t)SEG * NUP) : z; rg[SEG + 1] = hn ? *(const u32x2*)(hg + (size_t)SEG * NUP) : z; }
.LBB0_221:
	s_or_b64 exec, exec, s[0:1]
	v_add_co_u32_e32 v38, vcc, 0x1000, v100
	s_mov_b32 s0, 0x10000
	s_nop 0
	v_addc_co_u32_e32 v39, vcc, 0, v101, vcc
	v_add_co_u32_e32 v40, vcc, 0x2000, v100
	s_nop 1
	v_addc_co_u32_e32 v41, vcc, 0, v101, vcc
	v_add_co_u32_e32 v42, vcc, 0x4000, v100
	s_nop 1
	v_addc_co_u32_e32 v43, vcc, 0, v101, vcc
	global_load_dwordx2 v[108:109], v[100:101], off nt
	global_load_dwordx2 v[102:103], v[38:39], off offset:1536 nt
	global_load_dwordx2 v[106:107], v[40:41], off offset:3072 nt
	global_load_dwordx2 v[104:105], v[42:43], off offset:512 nt
	v_add_co_u32_e32 v38, vcc, 0x5000, v100
	s_nop 1
	v_addc_co_u32_e32 v39, vcc, 0, v101, vcc
	v_add_co_u32_e32 v40, vcc, 0x6000, v100
	s_nop 1
	v_addc_co_u32_e32 v41, vcc, 0, v101, vcc
	v_add_co_u32_e32 v42, vcc, 0x8000, v100
	s_nop 1
	v_addc_co_u32_e32 v43, vcc, 0, v101, vcc
	v_add_co_u32_e32 v44, vcc, 0x9000, v100
	s_nop 1
	v_addc_co_u32_e32 v45, vcc, 0, v101, vcc
	global_load_dwordx2 v[94:95], v[38:39], off offset:2048 nt
	global_load_dwordx2 v[92:93], v[40:41], off offset:3584 nt
	global_load_dwordx2 v[90:91], v[42:43], off offset:1024 nt
	global_load_dwordx2 v[88:89], v[44:45], off offset:2560 nt
	v_add_co_u32_e32 v38, vcc, 0xb000, v100
	s_nop 1
	v_addc_co_u32_e32 v39, vcc, 0, v101, vcc
	v_add_co_u32_e32 v40, vcc, 0xc000, v100
	s_nop 1
	v_addc_co_u32_e32 v41, vcc, 0, v101, vcc
	v_add_co_u32_e32 v42, vcc, 0xd000, v100
	s_nop 1
	v_addc_co_u32_e32 v43, vcc, 0, v101, vcc
	v_add_co_u32_e32 v44, vcc, 0xf000, v100
	s_nop 1
	v_addc_co_u32_e32 v45, vcc, 0, v101, vcc
	global_load_dwordx2 v[86:87], v[38:39], off nt
	global_load_dwordx2 v[84:85], v[40:41], off offset:1536 nt
	global_load_dwordx2 v[82:83], v[42:43], off offset:3072 nt
	global_load_dwordx2 v[80:81], v[44:45], off offset:512 nt
	v_add_co_u32_e32 v38, vcc, s0, v100
	s_mov_b32 s0, 0x14000
	s_nop 0
	v_addc_co_u32_e32 v39, vcc, 0, v101, vcc
	v_add_co_u32_e32 v40, vcc, 0x11000, v100
	s_nop 1
	v_addc_co_u32_e32 v41, vcc, 0, v101, vcc
	v_add_co_u32_e32 v42, vcc, 0x13000, v100
	s_nop 1
	v_addc_co_u32_e32 v43, vcc, 0, v101, vcc
	v_add_co_u32_e32 v44, vcc, s0, v100
	s_mov_b32 s0, 0x16000
	s_nop 0
	v_addc_co_u32_e32 v45, vcc, 0, v101, vcc
	global_load_dwordx2 v[78:79], v[38:39], off offset:2048 nt
	global_load_dwordx2 v[76:77], v[40:41], off offset:3584 nt
	global_load_dwordx2 v[74:75], v[42:43], off offset:1024 nt
	global_load_dwordx2 v[72:73], v[44:45], off offset:2560 nt
	v_add_co_u32_e32 v38, vcc, s0, v100
	s_mov_b32 s0, 0x18000
	s_nop 0
	v_addc_co_u32_e32 v39, vcc, 0, v101, vcc
	v_add_co_u32_e32 v40, vcc, 0x17000, v100
	s_nop 1
	v_addc_co_u32_e32 v41, vcc, 0, v101, vcc
	v_add_co_u32_e32 v42, vcc, s0, v100
	s_mov_b32 s0, 0x1a000
	s_nop 0
	v_addc_co_u32_e32 v43, vcc, 0, v101, vcc
	v_add_co_u32_e32 v44, vcc, s0, v100
	s_mov_b32 s0, 0x1c000
	s_nop 0
	v_addc_co_u32_e32 v45, vcc, 0, v101, vcc
	global_load_dwordx2 v[70:71], v[38:39], off nt
	global_load_dwordx2 v[68:69], v[40:41], off offset:1536 nt
	global_load_dwordx2 v[66:67], v[42:43], off offset:3072 nt
	global_load_dwordx2 v[64:65], v[44:45], off offset:512 nt
	v_add_co_u32_e32 v38, vcc, 0x1b000, v100
	s_nop 1
	v_addc_co_u32_e32 v39, vcc, 0, v101, vcc
	v_add_co_u32_e32 v40, vcc, s0, v100
	s_mov_b32 s0, 0x1e000
	s_nop 0
	v_addc_co_u32_e32 v41, vcc, 0, v101, vcc
	v_add_co_u32_e32 v42, vcc, s0, v100
	s_nop 1
	v_addc_co_u32_e32 v43, vcc, 0, v101, vcc
	v_add_co_u32_e32 v44, vcc, 0x1f000, v100
	s_nop 1
	v_addc_co_u32_e32 v45, vcc, 0, v101, vcc
	global_load_dwordx2 v[62:63], v[38:39], off offset:2048 nt
	global_load_dwordx2 v[60:61], v[40:41], off offset:3584 nt
	global_load_dwordx2 v[58:59], v[42:43], off offset:1024 nt
	global_load_dwordx2 v[56:57], v[44:45], off offset:2560 nt
	v_add_co_u32_e32 v38, vcc, 0x21000, v100
	s_nop 1
	v_addc_co_u32_e32 v39, vcc, 0, v101, vcc
	v_add_co_u32_e32 v40, vcc, 0x22000, v100
	s_nop 1
	v_addc_co_u32_e32 v41, vcc, 0, v101, vcc
	v_add_co_u32_e32 v42, vcc, 0x23000, v100
	s_nop 1
	v_addc_co_u32_e32 v43, vcc, 0, v101, vcc
	v_add_co_u32_e32 v44, vcc, 0x25000, v100
	s_nop 1
	v_addc_co_u32_e32 v45, vcc, 0, v101, vcc
	global_load_dwordx2 v[54:55], v[38:39], off nt
	global_load_dwordx2 v[52:53], v[40:41], off offset:1536 nt
	global_load_dwordx2 v[50:51], v[42:43], off offset:3072 nt
	global_load_dwordx2 v[48:49], v[44:45], off offset:512 nt
	v_add_co_u32_e32 v38, vcc, 0x26000, v100
	s_nop 1
	v_addc_co_u32_e32 v39, vcc, 0, v101, vcc
	v_add_co_u32_e32 v40, vcc, 0x27000, v100
	s_nop 1
	v_addc_co_u32_e32 v41, vcc, 0, v101, vcc
	v_add_co_u32_e32 v42, vcc, 0x29000, v100
	s_nop 1
	v_addc_co_u32_e32 v43, vcc, 0, v101, vcc
	v_add_co_u32_e32 v114, vcc, 0x2a000, v100
	s_nop 1
	v_addc_co_u32_e32 v115, vcc, 0, v101, vcc
	global_load_dwordx2 v[46:47], v[38:39], off offset:2048 nt
	global_load_dwordx2 v[44:45], v[40:41], off offset:3584 nt
	s_nop 0
	global_load_dwordx2 v[42:43], v[42:43], off offset:1024 nt
	s_nop 0
	global_load_dwordx2 v[40:41], v[114:115], off offset:2560 nt
	v_cmp_gt_i32_e32 vcc, s7, v35
	v_mov_b32_e32 v35, 0
	v_mov_b32_e32 v38, 0
	v_mov_b32_e32 v39, 0
	s_and_saveexec_b64 s[0:1], vcc
	s_cbranch_execz .LBB0_218
	v_add_co_u32_e32 v34, vcc, 0x2c000, v100
	s_nop 1
	v_addc_co_u32_e32 v35, vcc, 0, v101, vcc
	v_add_co_u32_e32 v38, vcc, 0x2d000, v100
	s_nop 1
	v_addc_co_u32_e32 v39, vcc, 0, v101, vcc
	global_load_dwordx2 v[34:35], v[34:35], off nt
	s_nop 0
	global_load_dwordx2 v[38:39], v[38:39], off offset:1536 nt
	s_branch .LBB0_218

; DI void phase_ln(const void* srcv, const int srcmode, const bf16_t* xres,
;                  const float* g, const float* b, float* dstf, bf16_t* dstb, int ntok, int tid,
;                  unsigned char* smem, const float* wg, const float* bias16, float* gpre) {
;     ...
;         if (row + rstride < ntok) LN_LOAD(row + rstride);
.LBB0_252:
	v_add_u32_e32 v66, s6, v66
	v_cmp_gt_i32_e32 vcc, s10, v66
	v_cmp_le_i32_e64 s[36:37], s10, v66
	s_and_saveexec_b64 s[18:19], vcc
	s_cbranch_execz .LBB0_254
	v_lshl_add_u64 v[34:35], v[70:71], 0, v[0:1]
	v_add_co_u32_e32 v34, vcc, 0x5110000, v34
	v_lshl_add_u64 v[42:43], v[72:73], 0, v[0:1]
	s_nop 0
	v_addc_co_u32_e32 v35, vcc, 0, v35, vcc
	global_load_dwordx4 v[38:41], v[34:35], off nt
	global_load_dwordx4 v[46:49], v[34:35], off offset:1024 nt
	s_nop 0
	global_load_dwordx4 v[34:37], v[42:43], off offset:-1024 nt
	s_nop 0
	global_load_dwordx4 v[42:45], v[42:43], off nt

; DI void phase_merge(const Params& p, int layer, int ntok, int tid) {
;     ...
;             if (row + rstride < ntok) MERGE_LOAD(row + rstride);
.LBB0_286:
	v_add_u32_e32 v162, s6, v162
	v_cmp_le_i32_e64 s[36:37], s10, v162
	v_cmp_gt_i32_e32 vcc, s10, v162
	s_or_b64 s[20:21], s[36:37], s[20:21]
	s_and_saveexec_b64 s[36:37], vcc
	s_cbranch_execz .LBB0_285
	v_lshl_add_u64 v[34:35], v[170:171], 0, v[0:1]
	s_mov_b64 s[2:3], 0x5110000
	v_lshl_add_u64 v[38:39], v[34:35], 0, s[2:3]
	v_add_co_u32_e32 v34, vcc, 0x5110000, v34
	v_lshl_add_u64 v[42:43], v[172:173], 0, v[0:1]
	s_nop 0
	v_addc_co_u32_e32 v35, vcc, 0, v35, vcc
	v_lshl_add_u64 v[46:47], v[42:43], 0, s[2:3]
	v_add_co_u32_e32 v42, vcc, 0x5110000, v42
	v_lshl_add_u64 v[54:55], v[174:175], 0, v[0:1]
	s_nop 0
	v_addc_co_u32_e32 v43, vcc, 0, v43, vcc
	v_lshl_add_u64 v[58:59], v[54:55], 0, s[2:3]
	v_add_co_u32_e32 v54, vcc, 0x5110000, v54
	v_lshl_add_u64 v[62:63], v[168:169], 0, v[0:1]
	s_nop 0
	v_addc_co_u32_e32 v55, vcc, 0, v55, vcc
	v_lshl_add_u64 v[66:67], v[62:63], 0, s[2:3]
	v_add_co_u32_e32 v62, vcc, 0x5110000, v62
	v_lshl_add_u64 v[90:91], v[166:167], 0, v[0:1]
	s_nop 0
	v_addc_co_u32_e32 v63, vcc, 0, v63, vcc
	v_lshl_add_u64 v[70:71], v[90:91], 0, s[2:3]
	v_add_co_u32_e32 v78, vcc, 0x5110000, v90
	s_mov_b64 s[2:3], 0x5110800
	s_nop 0
	v_addc_co_u32_e32 v79, vcc, 0, v91, vcc
	v_lshl_add_u64 v[82:83], v[90:91], 0, s[2:3]
	s_mov_b64 s[2:3], 0x5111000
	v_lshl_add_u64 v[86:87], v[90:91], 0, s[2:3]
	v_add_co_u32_e32 v94, vcc, 0x5111000, v90
	s_mov_b64 s[2:3], 0x5111800
	s_nop 0
	v_addc_co_u32_e32 v95, vcc, 0, v91, vcc
	v_lshl_add_u64 v[98:99], v[90:91], 0, s[2:3]
	global_load_dwordx4 v[34:37], v[34:35], off nt
	s_nop 0
	global_load_dwordx4 v[38:41], v[38:39], off offset:16 nt
	s_nop 0
	global_load_dwordx4 v[42:45], v[42:43], off nt
	s_nop 0
	global_load_dwordx4 v[46:49], v[46:47], off offset:16 nt
	s_nop 0
	global_load_dwordx4 v[54:57], v[54:55], off nt
	s_nop 0
	global_load_dwordx4 v[58:61], v[58:59], off offset:16 nt
	s_nop 0
	global_load_dwordx4 v[62:65], v[62:63], off nt
	s_nop 0
	global_load_dwordx4 v[66:69], v[66:67], off offset:16 nt
	s_nop 0
	global_load_dwordx4 v[70:73], v[70:71], off offset:16 nt
	s_nop 0
	global_load_dwordx4 v[74:77], v[78:79], off nt
	s_nop 0
	global_load_dwordx4 v[78:81], v[78:79], off offset:2048 nt
	s_nop 0
	global_load_dwordx4 v[82:85], v[82:83], off offset:16 nt
	s_nop 0
	global_load_dwordx4 v[86:89], v[86:87], off offset:16 nt
	s_nop 0
	global_load_dwordx4 v[90:93], v[94:95], off nt
	s_nop 0
	global_load_dwordx4 v[94:97], v[94:95], off offset:2048 nt
	s_nop 0
	global_load_dwordx4 v[98:101], v[98:99], off offset:16 nt
	s_branch .LBB0_285
